# hazard-hardened mask block moved out of line (rare path); hot softmax path unchanged
# baseline (speedup 1.0000x reference)
; __device__ __forceinline__ void attn_unit(KParams& P, int l, const AUnit& U, LAS unsigned char* lds) {
;     ...
;         if ((t + 1) * 64 > U.kvlen) {
;             const int kb0 = t * 64 + 8 * hi;
; #pragma unroll
;             for (int r = 0; r < 16; ++r) { const int kv = kb0 + 16 * (r >> 3) + (r & 7); if (kv >= U.kvlen) p0[r] = -INFINITY; if (kv + 32 >= U.kvlen) p1[r] = -INFINITY; }
;         }
.Lattn_noload_y:
	s_nop 7
	s_lshl_b32 s25, s20, 6
	s_add_i32 s28, s25, 64
	s_cmp_le_u32 s28, s70
	s_cbranch_scc0 .Lattn_mask

; __device__ __forceinline__ void attn_unit(KParams& P, int l, const AUnit& U, LAS unsigned char* lds) {
;     ...
;         if ((t + 1) * 64 > U.kvlen) {
;             const int kb0 = t * 64 + 8 * hi;
; #pragma unroll
;             for (int r = 0; r < 16; ++r) { const int kv = kb0 + 16 * (r >> 3) + (r & 7); if (kv >= U.kvlen) p0[r] = -INFINITY; if (kv + 32 >= U.kvlen) p1[r] = -INFINITY; }
;         }
.Lattn_mask:
	v_add_u32_e32 v208, s25, v164
	v_add_u32_e32 v209, 0, v208
	v_cmp_gt_u32_e32 vcc, s70, v209
	s_nop 1
	v_cndmask_b32_e32 v80, v225, v80, vcc
	v_add_u32_e32 v209, 32, v208
	v_cmp_gt_u32_e32 vcc, s70, v209
	s_nop 1
	v_cndmask_b32_e32 v64, v225, v64, vcc
	v_add_u32_e32 v209, 1, v208
	v_cmp_gt_u32_e32 vcc, s70, v209
	s_nop 1
	v_cndmask_b32_e32 v81, v225, v81, vcc
	v_add_u32_e32 v209, 33, v208
	v_cmp_gt_u32_e32 vcc, s70, v209
	s_nop 1
	v_cndmask_b32_e32 v65, v225, v65, vcc
	v_add_u32_e32 v209, 2, v208
	v_cmp_gt_u32_e32 vcc, s70, v209
	s_nop 1
	v_cndmask_b32_e32 v82, v225, v82, vcc
	v_add_u32_e32 v209, 34, v208
	v_cmp_gt_u32_e32 vcc, s70, v209
	s_nop 1
	v_cndmask_b32_e32 v66, v225, v66, vcc
	v_add_u32_e32 v209, 3, v208
	v_cmp_gt_u32_e32 vcc, s70, v209
	s_nop 1
	v_cndmask_b32_e32 v83, v225, v83, vcc
	v_add_u32_e32 v209, 35, v208
	v_cmp_gt_u32_e32 vcc, s70, v209
	s_nop 1
	v_cndmask_b32_e32 v67, v225, v67, vcc
	v_add_u32_e32 v209, 4, v208
	v_cmp_gt_u32_e32 vcc, s70, v209
	s_nop 1
	v_cndmask_b32_e32 v84, v225, v84, vcc
	v_add_u32_e32 v209, 36, v208
	v_cmp_gt_u32_e32 vcc, s70, v209
	s_nop 1
	v_cndmask_b32_e32 v68, v225, v68, vcc
	v_add_u32_e32 v209, 5, v208
	v_cmp_gt_u32_e32 vcc, s70, v209
	s_nop 1
	v_cndmask_b32_e32 v85, v225, v85, vcc
	v_add_u32_e32 v209, 37, v208
	v_cmp_gt_u32_e32 vcc, s70, v209
	s_nop 1
	v_cndmask_b32_e32 v69, v225, v69, vcc
	v_add_u32_e32 v209, 6, v208
	v_cmp_gt_u32_e32 vcc, s70, v209
	s_nop 1
	v_cndmask_b32_e32 v86, v225, v86, vcc
	v_add_u32_e32 v209, 38, v208
	v_cmp_gt_u32_e32 vcc, s70, v209
	s_nop 1
	v_cndmask_b32_e32 v70, v225, v70, vcc
	v_add_u32_e32 v209, 7, v208
	v_cmp_gt_u32_e32 vcc, s70, v209
	s_nop 1
	v_cndmask_b32_e32 v87, v225, v87, vcc
	v_add_u32_e32 v209, 39, v208
	v_cmp_gt_u32_e32 vcc, s70, v209
	s_nop 1
	v_cndmask_b32_e32 v71, v225, v71, vcc
	v_add_u32_e32 v209, 16, v208
	v_cmp_gt_u32_e32 vcc, s70, v209
	s_nop 1
	v_cndmask_b32_e32 v88, v225, v88, vcc
	v_add_u32_e32 v209, 48, v208
	v_cmp_gt_u32_e32 vcc, s70, v209
	s_nop 1
	v_cndmask_b32_e32 v72, v225, v72, vcc
	v_add_u32_e32 v209, 17, v208
	v_cmp_gt_u32_e32 vcc, s70, v209
	s_nop 1
	v_cndmask_b32_e32 v89, v225, v89, vcc
	v_add_u32_e32 v209, 49, v208
	v_cmp_gt_u32_e32 vcc, s70, v209
	s_nop 1
	v_cndmask_b32_e32 v73, v225, v73, vcc
	v_add_u32_e32 v209, 18, v208
	v_cmp_gt_u32_e32 vcc, s70, v209
	s_nop 1
	v_cndmask_b32_e32 v90, v225, v90, vcc
	v_add_u32_e32 v209, 50, v208
	v_cmp_gt_u32_e32 vcc, s70, v209
	s_nop 1
	v_cndmask_b32_e32 v74, v225, v74, vcc
	v_add_u32_e32 v209, 19, v208
	v_cmp_gt_u32_e32 vcc, s70, v209
	s_nop 1
	v_cndmask_b32_e32 v91, v225, v91, vcc
	v_add_u32_e32 v209, 51, v208
	v_cmp_gt_u32_e32 vcc, s70, v209
	s_nop 1
	v_cndmask_b32_e32 v75, v225, v75, vcc
	v_add_u32_e32 v209, 20, v208
	v_cmp_gt_u32_e32 vcc, s70, v209
	s_nop 1
	v_cndmask_b32_e32 v92, v225, v92, vcc
	v_add_u32_e32 v209, 52, v208
	v_cmp_gt_u32_e32 vcc, s70, v209
	s_nop 1
	v_cndmask_b32_e32 v76, v225, v76, vcc
	v_add_u32_e32 v209, 21, v208
	v_cmp_gt_u32_e32 vcc, s70, v209
	s_nop 1
	v_cndmask_b32_e32 v93, v225, v93, vcc
	v_add_u32_e32 v209, 53, v208
	v_cmp_gt_u32_e32 vcc, s70, v209
	s_nop 1
	v_cndmask_b32_e32 v77, v225, v77, vcc
	v_add_u32_e32 v209, 22, v208
	v_cmp_gt_u32_e32 vcc, s70, v209
	s_nop 1
	v_cndmask_b32_e32 v94, v225, v94, vcc
	v_add_u32_e32 v209, 54, v208
	v_cmp_gt_u32_e32 vcc, s70, v209
	s_nop 1
	v_cndmask_b32_e32 v78, v225, v78, vcc
	v_add_u32_e32 v209, 23, v208
	v_cmp_gt_u32_e32 vcc, s70, v209
	s_nop 1
	v_cndmask_b32_e32 v95, v225, v95, vcc
	v_add_u32_e32 v209, 55, v208
	v_cmp_gt_u32_e32 vcc, s70, v209
	s_nop 1
	v_cndmask_b32_e32 v79, v225, v79, vcc
	s_branch .Lattn_nomask
